# hgrn chunk output stage: one wait for the gate loads at the first row block, no counted waits that serialise on the stage's own stores
# speedup vs baseline: 1.0037x; 1.0010x over previous
; __device__ __forceinline__ void item_hgrn(const Params& p, int l, int sidx) {
;     ...
; #pragma unroll
;     for (int j = 0; j < 4; ++j) {
;       int tl = tt * 16 + fq * 4 + j;
;       if (t0 + tl < T) {
;         float ss = ssq[tl] + ssq[64 + tl];
;         float rstd = rsqrtf(ss * (1.f / 128.f) + EPSV);
; #pragma unroll
;         for (int n = 0; n < 4; ++n) {
;           int dv = dvh * 64 + n * 16 + fr;
;           long idx = (long)(tok0 + t0 + tl) * 512 + hh * 128 + dv;
;           float g = __uint_as_float(gzr[j][n] << 16);
;           p.gzb[idx] = f2bf(oacc[n][j] * rstd * hgv[n] * g);
;         }
;       }
;     }
.LBB0_828:
	ds_read2st64_b32 v[206:207], v145 offset1:1
	s_waitcnt vmcnt(0)
	v_lshlrev_b32_e32 v221, 16, v204
	v_lshlrev_b32_e32 v220, 16, v205
	v_add_u32_e32 v218, s83, v156
	v_ashrrev_i32_e32 v219, 31, v218
	s_waitcnt lgkmcnt(0)
	v_add_f32_e32 v204, v206, v207
	v_fmamk_f32 v204, v204, 0x3c000000, v192
	v_mul_f32_e32 v205, 0x4b800000, v204
	v_cmp_gt_f32_e32 vcc, s30, v204
	s_nop 1
	v_cndmask_b32_e32 v204, v204, v205, vcc
	v_rsq_f32_e32 v206, v204
	v_lshlrev_b64 v[204:205], 10, v[218:219]
	v_lshl_add_u64 v[204:205], v[80:81], 0, v[204:205]
	v_mul_f32_e32 v207, 0x45800000, v206
	v_cndmask_b32_e32 v206, v206, v207, vcc
	v_mul_f32_e32 v40, v40, v206
	v_mul_f32_e32 v40, v69, v40
	v_mul_f32_e32 v40, v40, v220
	v_bfe_u32 v207, v40, 16, 1
	v_add3_u32 v40, v40, v207, s80
	global_store_short_d16_hi v[204:205], v40, off
	v_mul_f32_e32 v40, v44, v206
	v_mul_f32_e32 v40, v71, v40
	v_mul_f32_e32 v40, v40, v221
	v_bfe_u32 v44, v40, 16, 1
	v_add3_u32 v40, v40, v44, s80
	v_mul_f32_e32 v44, v48, v206
	global_store_short_d16_hi v[204:205], v40, off offset:32
	v_lshlrev_b32_e32 v40, 16, v203
	v_mul_f32_e32 v44, v73, v44
	v_mul_f32_e32 v40, v44, v40
	v_bfe_u32 v44, v40, 16, 1
	v_add3_u32 v40, v40, v44, s80
	v_mul_f32_e32 v44, v52, v206
	global_store_short_d16_hi v[204:205], v40, off offset:64
	v_lshlrev_b32_e32 v40, 16, v202
	v_mul_f32_e32 v44, v75, v44
	v_mul_f32_e32 v40, v44, v40
	v_bfe_u32 v44, v40, 16, 1
	v_add3_u32 v40, v40, v44, s80
	global_store_short_d16_hi v[204:205], v40, off offset:96
	s_or_b64 exec, exec, s[28:29]
	v_cmp_gt_u32_e32 vcc, s86, v201
	s_and_saveexec_b64 s[28:29], vcc
	s_cbranch_execz .LBB0_826
.LBB0_829:
	ds_read2st64_b32 v[202:203], v146 offset1:1
	v_add3_u32 v204, v156, s83, 1
	v_lshlrev_b32_e32 v40, 16, v200
	v_ashrrev_i32_e32 v205, 31, v204
	v_lshlrev_b64 v[200:201], 10, v[204:205]
	s_waitcnt lgkmcnt(0)
	v_add_f32_e32 v48, v202, v203
	v_fmamk_f32 v48, v48, 0x3c000000, v192
	v_mul_f32_e32 v52, 0x4b800000, v48
	v_cmp_gt_f32_e32 vcc, s30, v48
	v_lshl_add_u64 v[200:201], v[80:81], 0, v[200:201]
	v_lshlrev_b32_e32 v44, 16, v199
	v_cndmask_b32_e32 v48, v48, v52, vcc
	v_rsq_f32_e32 v48, v48
	s_nop 0
	v_mul_f32_e32 v52, 0x45800000, v48
	v_cndmask_b32_e32 v48, v48, v52, vcc
	v_mul_f32_e32 v41, v41, v48
	v_mul_f32_e32 v41, v69, v41
	v_mul_f32_e32 v40, v41, v40
	v_bfe_u32 v41, v40, 16, 1
	v_add3_u32 v40, v40, v41, s80
	global_store_short_d16_hi v[200:201], v40, off
	v_mul_f32_e32 v40, v45, v48
	v_mul_f32_e32 v40, v71, v40
	v_mul_f32_e32 v40, v40, v44
	v_bfe_u32 v41, v40, 16, 1
	v_add3_u32 v40, v40, v41, s80
	v_mul_f32_e32 v41, v49, v48
	global_store_short_d16_hi v[200:201], v40, off offset:32
	v_lshlrev_b32_e32 v40, 16, v190
	v_mul_f32_e32 v41, v73, v41
	v_mul_f32_e32 v40, v41, v40
	v_bfe_u32 v41, v40, 16, 1
	v_add3_u32 v40, v40, v41, s80
	v_mul_f32_e32 v41, v53, v48
	global_store_short_d16_hi v[200:201], v40, off offset:64
	v_lshlrev_b32_e32 v40, 16, v187
	v_mul_f32_e32 v41, v75, v41
	v_mul_f32_e32 v40, v41, v40
	v_bfe_u32 v41, v40, 16, 1
	v_add3_u32 v40, v40, v41, s80
	global_store_short_d16_hi v[200:201], v40, off offset:96
	s_or_b64 exec, exec, s[28:29]
	v_cmp_gt_u32_e32 vcc, s86, v186
	s_and_saveexec_b64 s[28:29], vcc
	s_cbranch_execz .LBB0_827
.LBB0_830:
	ds_read2st64_b32 v[40:41], v147 offset1:1
	v_add3_u32 v44, v156, s83, 2
	v_ashrrev_i32_e32 v45, 31, v44
	v_lshlrev_b32_e32 v48, 16, v185
	v_lshlrev_b32_e32 v49, 16, v184
	s_waitcnt lgkmcnt(0)
	v_add_f32_e32 v40, v40, v41
	v_fmamk_f32 v40, v40, 0x3c000000, v192
	v_mul_f32_e32 v41, 0x4b800000, v40
	v_cmp_gt_f32_e32 vcc, s30, v40
	s_nop 1
	v_cndmask_b32_e32 v40, v40, v41, vcc
	v_rsq_f32_e32 v52, v40
	v_lshlrev_b64 v[40:41], 10, v[44:45]
	v_lshl_add_u64 v[40:41], v[80:81], 0, v[40:41]
	v_mul_f32_e32 v44, 0x45800000, v52
	v_cndmask_b32_e32 v44, v52, v44, vcc
	v_mul_f32_e32 v42, v42, v44
	v_mul_f32_e32 v42, v69, v42
	v_mul_f32_e32 v42, v42, v48
	v_bfe_u32 v45, v42, 16, 1
	v_add3_u32 v42, v42, v45, s80
	global_store_short_d16_hi v[40:41], v42, off
	v_mul_f32_e32 v42, v46, v44
	v_mul_f32_e32 v42, v71, v42
	v_mul_f32_e32 v42, v42, v49
	v_bfe_u32 v45, v42, 16, 1
	v_add3_u32 v42, v42, v45, s80
	v_mul_f32_e32 v45, v50, v44
	global_store_short_d16_hi v[40:41], v42, off offset:32
	v_lshlrev_b32_e32 v42, 16, v183
	v_mul_f32_e32 v45, v73, v45
	v_mul_f32_e32 v42, v45, v42
	v_bfe_u32 v45, v42, 16, 1
	v_add3_u32 v42, v42, v45, s80
	v_mul_f32_e32 v44, v54, v44
	global_store_short_d16_hi v[40:41], v42, off offset:64
	v_lshlrev_b32_e32 v42, 16, v182
	v_mul_f32_e32 v44, v75, v44
	v_mul_f32_e32 v42, v44, v42
	v_bfe_u32 v44, v42, 16, 1
	v_add3_u32 v42, v42, v44, s80
	global_store_short_d16_hi v[40:41], v42, off offset:96
	s_or_b64 exec, exec, s[28:29]
	v_cmp_gt_u32_e32 vcc, s86, v181
	s_and_saveexec_b64 s[28:29], vcc
	s_cbranch_execz .LBB0_801
.LBB0_831:
	ds_read2st64_b32 v[40:41], v148 offset1:1
	v_add3_u32 v44, v156, s83, 3
	v_ashrrev_i32_e32 v45, 31, v44
	v_lshlrev_b32_e32 v42, 16, v180
	v_lshlrev_b32_e32 v46, 16, v179
	s_waitcnt lgkmcnt(0)
	v_add_f32_e32 v40, v40, v41
	v_fmamk_f32 v40, v40, 0x3c000000, v192
	v_mul_f32_e32 v41, 0x4b800000, v40
	v_cmp_gt_f32_e32 vcc, s30, v40
	s_nop 1
	v_cndmask_b32_e32 v40, v40, v41, vcc
	v_rsq_f32_e32 v48, v40
	v_lshlrev_b64 v[40:41], 10, v[44:45]
	v_lshl_add_u64 v[40:41], v[80:81], 0, v[40:41]
	v_mul_f32_e32 v44, 0x45800000, v48
	v_cndmask_b32_e32 v44, v48, v44, vcc
	v_mul_f32_e32 v43, v43, v44
	v_mul_f32_e32 v43, v69, v43
	v_mul_f32_e32 v42, v43, v42
	v_bfe_u32 v43, v42, 16, 1
	v_add3_u32 v42, v42, v43, s80
	global_store_short_d16_hi v[40:41], v42, off
	v_mul_f32_e32 v42, v47, v44
	v_mul_f32_e32 v42, v71, v42
	v_mul_f32_e32 v42, v42, v46
	v_bfe_u32 v43, v42, 16, 1
	v_add3_u32 v42, v42, v43, s80
	v_mul_f32_e32 v43, v51, v44
	global_store_short_d16_hi v[40:41], v42, off offset:32
	v_lshlrev_b32_e32 v42, 16, v178
	v_mul_f32_e32 v43, v73, v43
	v_mul_f32_e32 v42, v43, v42
	v_bfe_u32 v43, v42, 16, 1
	v_add3_u32 v42, v42, v43, s80
	v_mul_f32_e32 v43, v55, v44
	global_store_short_d16_hi v[40:41], v42, off offset:64
	v_lshlrev_b32_e32 v42, 16, v177
	v_mul_f32_e32 v43, v75, v43
	v_mul_f32_e32 v42, v43, v42
	v_bfe_u32 v43, v42, 16, 1
	v_add3_u32 v42, v42, v43, s80
	global_store_short_d16_hi v[40:41], v42, off offset:96
	s_branch .LBB0_801
